# split-update version with the substitution's cross-lane move done by v_permlane16_swap (no lgkmcnt wait inside the MFMA stream)
# baseline (speedup 1.0000x reference)
.Lmy_f_main:
	s_cmpk_ge_u32 s62, 0x100
	s_cbranch_scc1 .Lmy_f_hlp
	s_cmp_lg_u32 s65, 0
	s_cbranch_scc1 .Lmy_ck_nz
	v_mov_b32_e32 v208, 0
	v_mov_b32_e32 v209, 0
	v_mov_b32_e32 v210, 0
	v_mov_b32_e32 v211, 0
	v_mov_b32_e32 v212, 0
	v_mov_b32_e32 v213, 0
	v_mov_b32_e32 v214, 0
	v_mov_b32_e32 v215, 0
	v_mov_b32_e32 v216, 0
	v_mov_b32_e32 v217, 0
	v_mov_b32_e32 v218, 0
	v_mov_b32_e32 v219, 0
	v_mov_b32_e32 v220, 0
	v_mov_b32_e32 v221, 0
	v_mov_b32_e32 v222, 0
	v_mov_b32_e32 v223, 0
	v_mov_b32_e32 v204, 0
	v_mov_b32_e32 v205, 0
	v_mov_b32_e32 v206, 0
	v_mov_b32_e32 v207, 0
	v_xor_b32_e32 v1, v224, v234
	v_lshlrev_b32_e32 v1, 4, v1
	v_lshlrev_b32_e32 v2, 4, v234
	v_add_u32_e32 v2, 0x2000, v2
	v_mov_b32_e32 v72, 0x2600
	v_mov_b32_e32 v73, 0x2500
	v_mov_b32_e32 v74, 0x2510
	v_mov_b32_e32 v75, 0x2590
	v_cmp_eq_u32_e64 s[96:97], 0, v234
	v_and_b32_e32 v76, 1, v234
	v_lshrrev_b32_e32 v77, 1, v234
	v_cndmask_b32_e64 v3, v72, v73, s[96:97]
	v_cmp_eq_u32_e64 s[96:97], 1, v234
	v_and_b32_e32 v78, 1, v234
	v_add_u32_e32 v79, 2, v77
	v_cndmask_b32_e64 v4, v72, v74, s[96:97]
	v_cndmask_b32_e64 v5, v72, v75, s[96:97]
	v_lshlrev_b32_e32 v76, 10, v76
	v_lshl_add_u32 v76, v233, 2, v76
	v_add_u32_e32 v8, s62, v76
	v_lshlrev_b32_e32 v76, 9, v234
	v_lshl_add_u32 v76, v233, 2, v76
	v_add_u32_e32 v9, s62, v76
	v_lshl_add_u32 v6, v79, 4, v233
	v_xor_b32_e32 v6, v6, v79
	v_lshlrev_b32_e32 v6, 4, v6
	v_lshl_add_u32 v6, v78, 3, v6
	v_add_u32_e32 v6, 0x2100, v6
	v_lshl_add_u32 v7, v78, 4, v233
	v_xor_b32_e32 v7, v7, v78
	v_lshlrev_b32_e32 v7, 4, v7
	v_lshl_add_u32 v7, v77, 3, v7
	v_add_u32_e32 v7, 0x2100, v7
	v_lshlrev_b32_e32 v0, 4, v233
	v_lshl_add_u32 v0, v78, 8, v0
	v_lshl_add_u32 v0, v77, 3, v0
	v_add_u32_e32 v0, 0x1000, v0
	v_lshlrev_b32_e32 v10, 4, v233
	v_lshl_add_u32 v10, v79, 8, v10
	v_lshl_add_u32 v10, v78, 3, v10
	v_add_u32_e32 v10, 0x1000, v10
	v_add_u32_e32 v232, 48, v224
	v_and_b32_e32 v232, 63, v232
	v_lshlrev_b32_e32 v232, 2, v232
.Lmy_ck_nz:
	s_mov_b32 s100, 0xe000
	s_cmp_eq_u32 s23, 0
	s_cselect_b32 s100, 0x1c000, s100
	s_mov_b32 s101, 0x12e00
	s_cselect_b32 s101, 0x22100, s101
	s_lshl_b32 s96, s23, 13
	s_add_i32 s97, s96, 0x18000
	s_add_i32 s96, s96, 0xa000
	v_add_u32_e32 v225, s100, v1
	v_add_u32_e32 v236, s100, v0
	v_add_u32_e32 v34, s100, v10
	v_add_u32_e32 v226, s100, v2
	v_add_u32_e32 v227, s100, v3
	v_add_u32_e32 v228, s100, v4
	v_add_u32_e32 v229, s100, v5
	v_add_u32_e32 v237, s100, v6
	v_add_u32_e32 v238, s100, v7
	v_add_u32_e32 v230, s96, v8
	v_add_u32_e32 v239, s96, v9
	v_add_u32_e32 v231, s97, v8
	v_add_u32_e32 v26, s101, v1
	v_add_u32_e32 v27, s101, v0
	v_add_u32_e32 v35, s101, v10
	v_add_u32_e32 v28, s101, v2
	v_add_u32_e32 v29, s101, v3
	v_add_u32_e32 v30, s101, v4
	v_add_u32_e32 v31, s101, v5
	v_add_u32_e32 v32, s101, v6
	v_add_u32_e32 v33, s101, v7
	ds_read_b64 v[80:81], v237
	ds_read_b64 v[82:83], v238
	ds_read_b32 v36, v239
	ds_read_b32 v37, v239 offset:256
	ds_read_b128 v[88:91], v225
	ds_read_b128 v[92:95], v225 offset:1024
	ds_read_b128 v[96:99], v225 offset:2048
	ds_read_b128 v[100:103], v225 offset:3072
	ds_read_b32 v104, v227 offset:4
	ds_read_b32 v105, v227 offset:76
	ds_read_b64 v[106:107], v227 offset:8
	ds_read_b64 v[108:109], v227 offset:40
	ds_read_b32 v126, v229 offset:4
	ds_read_b32 v127, v229 offset:76
	ds_read_b64 v[128:129], v229 offset:8
	ds_read_b64 v[130:131], v229 offset:40
	ds_read_b64 v[110:111], v228
	ds_read_b64 v[112:113], v228 offset:32
	ds_read_b64 v[114:115], v228 offset:64
	ds_read_b64 v[116:117], v228 offset:96
	ds_read_b64 v[118:119], v228 offset:8
	ds_read_b64 v[120:121], v228 offset:40
	ds_read_b64 v[122:123], v228 offset:72
	ds_read_b64 v[124:125], v228 offset:104
	s_waitcnt lgkmcnt(15)
	v_mfma_f32_16x16x4_f32 v[240:243], v80, v36, 0
	v_mfma_f32_16x16x4_f32 v[240:243], v81, v37, v[240:243]
	v_mfma_f32_16x16x4_f32 v[240:243], v88, v208, v[240:243]
	ds_read_b64 v[186:187], v34
	ds_read_b64 v[190:191], v34 offset:1024
	v_mfma_f32_16x16x4_f32 v[244:247], v89, v209, 0
	ds_read_b64 v[194:195], v34 offset:2048
	ds_read_b64 v[198:199], v34 offset:3072
	v_mfma_f32_16x16x4_f32 v[240:243], v90, v210, v[240:243]
	ds_read_b64 v[184:185], v236
	ds_read_b64 v[188:189], v236 offset:1024
	ds_read_b64 v[132:133], v237 offset:9984
	v_mfma_f32_16x16x4_f32 v[244:247], v91, v211, v[244:247]
	ds_read_b64 v[134:135], v238 offset:9984
	ds_read_b64 v[192:193], v236 offset:2048
	ds_read_b64 v[196:197], v236 offset:3072
	v_mfma_f32_16x16x4_f32 v[240:243], v92, v212, v[240:243]
	ds_read_b32 v38, v239 offset:2048
	ds_read_b32 v39, v239 offset:2304
	ds_read_b128 v[140:143], v225 offset:9984
	v_mfma_f32_16x16x4_f32 v[244:247], v93, v213, v[244:247]
	ds_read_b128 v[144:147], v225 offset:11008
	ds_read_b128 v[148:151], v225 offset:12032
	ds_read_b128 v[152:155], v225 offset:13056
	v_mfma_f32_16x16x4_f32 v[240:243], v94, v214, v[240:243]
	ds_read_b32 v156, v227 offset:9988
	ds_read_b32 v157, v227 offset:10060
	v_mfma_f32_16x16x4_f32 v[244:247], v95, v215, v[244:247]
	ds_read_b64 v[158:159], v227 offset:9992
	ds_read_b64 v[160:161], v227 offset:10024
	v_mfma_f32_16x16x4_f32 v[240:243], v96, v216, v[240:243]
	ds_read_b32 v178, v229 offset:9988
	ds_read_b32 v179, v229 offset:10060
	v_mfma_f32_16x16x4_f32 v[244:247], v97, v217, v[244:247]
	ds_read_b64 v[180:181], v229 offset:9992
	ds_read_b64 v[182:183], v229 offset:10024
	v_mfma_f32_16x16x4_f32 v[240:243], v98, v218, v[240:243]
	ds_read_b64 v[162:163], v228 offset:9984
	ds_read_b64 v[164:165], v228 offset:10016
	v_mfma_f32_16x16x4_f32 v[244:247], v99, v219, v[244:247]
	ds_read_b64 v[166:167], v228 offset:10048
	ds_read_b64 v[168:169], v228 offset:10080
	v_mfma_f32_16x16x4_f32 v[240:243], v100, v220, v[240:243]
	ds_read_b64 v[170:171], v228 offset:9992
	ds_read_b64 v[172:173], v228 offset:10024
	v_mfma_f32_16x16x4_f32 v[244:247], v101, v221, v[244:247]
	ds_read_b64 v[174:175], v228 offset:10056
	ds_read_b64 v[176:177], v228 offset:10088
	v_mfma_f32_16x16x4_f32 v[240:243], v102, v222, v[240:243]
	v_mfma_f32_16x16x4_f32 v[244:247], v103, v223, v[244:247]
	s_waitcnt lgkmcnt(15)
	v_mfma_f32_16x16x4_f32 v[208:211], v186, v36, v[208:211]
	s_nop 2
	v_pk_add_f32 v[240:241], v[240:241], v[244:245]
	v_pk_add_f32 v[242:243], v[242:243], v[246:247]
	v_fmac_f32_e32 v241, v104, v240
	v_mfma_f32_16x16x4_f32 v[212:215], v190, v36, v[212:215]
	v_pk_fma_f32 v[242:243], v[106:107], v[240:241], v[242:243] op_sel:[0,0,0] op_sel_hi:[1,0,1]
	v_pk_fma_f32 v[242:243], v[108:109], v[240:241], v[242:243] op_sel:[0,1,0] op_sel_hi:[1,1,1]
	v_fmac_f32_e32 v243, v105, v242
	v_mfma_f32_16x16x4_f32 v[216:219], v194, v36, v[216:219]
	v_mov_b32_e32 v44, v240
	v_mov_b32_e32 v45, v241
	v_mov_b32_e32 v60, v242
	v_mfma_f32_16x16x4_f32 v[72:75], v132, v38, 0
	v_mov_b32_e32 v61, v243
	v_permlane16_swap_b32_e32 v204, v44
	v_permlane16_swap_b32_e32 v205, v45
	v_mfma_f32_16x16x4_f32 v[72:75], v133, v39, v[72:75]
	v_permlane16_swap_b32_e32 v206, v60
	v_permlane16_swap_b32_e32 v207, v61
	v_pk_fma_f32 v[240:241], v[110:111], v[204:205], v[240:241] op_sel:[0,0,0] op_sel_hi:[1,0,1]
	v_mfma_f32_16x16x4_f32 v[220:223], v198, v36, v[220:223]
	v_pk_fma_f32 v[240:241], v[112:113], v[204:205], v[240:241] op_sel:[0,1,0] op_sel_hi:[1,1,1]
	v_pk_fma_f32 v[240:241], v[114:115], v[206:207], v[240:241] op_sel:[0,0,0] op_sel_hi:[1,0,1]
	v_pk_fma_f32 v[240:241], v[116:117], v[206:207], v[240:241] op_sel:[0,1,0] op_sel_hi:[1,1,1]
	v_mfma_f32_16x16x4_f32 v[208:211], v187, v37, v[208:211]
	v_pk_fma_f32 v[242:243], v[118:119], v[204:205], v[242:243] op_sel:[0,0,0] op_sel_hi:[1,0,1]
	v_pk_fma_f32 v[242:243], v[120:121], v[204:205], v[242:243] op_sel:[0,1,0] op_sel_hi:[1,1,1]
	v_pk_fma_f32 v[242:243], v[122:123], v[206:207], v[242:243] op_sel:[0,0,0] op_sel_hi:[1,0,1]
	v_mfma_f32_16x16x4_f32 v[212:215], v191, v37, v[212:215]
	v_pk_fma_f32 v[242:243], v[124:125], v[206:207], v[242:243] op_sel:[0,1,0] op_sel_hi:[1,1,1]
	v_fmac_f32_e32 v241, v126, v240
	v_pk_fma_f32 v[242:243], v[128:129], v[240:241], v[242:243] op_sel:[0,0,0] op_sel_hi:[1,0,1]
	v_mfma_f32_16x16x4_f32 v[216:219], v195, v37, v[216:219]
	v_pk_fma_f32 v[242:243], v[130:131], v[240:241], v[242:243] op_sel:[0,1,0] op_sel_hi:[1,1,1]
	v_fmac_f32_e32 v243, v127, v242
	v_mov_b32_e32 v252, v240
	v_mfma_f32_16x16x4_f32 v[220:223], v199, v37, v[220:223]
	v_mov_b32_e32 v253, v241
	v_mov_b32_e32 v254, v242
	v_mov_b32_e32 v255, v243
	s_nop 0
	v_permlane32_swap_b32_e32 v252, v254
	v_permlane32_swap_b32_e32 v253, v255
	s_nop 0
	v_mfma_f32_16x16x4_f32 v[208:211], v184, v252, v[208:211]
	ds_read_b128 v[88:91], v226
	v_mfma_f32_16x16x4_f32 v[212:215], v188, v252, v[212:215]
	ds_read_b128 v[92:95], v226 offset:64
	v_mfma_f32_16x16x4_f32 v[216:219], v192, v252, v[216:219]
	ds_read_b128 v[96:99], v226 offset:128
	v_mfma_f32_16x16x4_f32 v[220:223], v196, v252, v[220:223]
	ds_read_b128 v[100:103], v226 offset:192
	v_mfma_f32_16x16x4_f32 v[208:211], v185, v253, v[208:211]
	v_mfma_f32_16x16x4_f32 v[212:215], v189, v253, v[212:215]
	v_mfma_f32_16x16x4_f32 v[216:219], v193, v253, v[216:219]
	v_mfma_f32_16x16x4_f32 v[220:223], v197, v253, v[220:223]
	v_mfma_f32_16x16x4_f32 v[248:251], v82, v252, v[240:243]
	v_mfma_f32_16x16x4_f32 v[248:251], v83, v253, v[248:251]
	s_waitcnt lgkmcnt(3)
	v_pk_mul_f32 v[208:209], v[208:209], v[88:89]
	v_pk_mul_f32 v[210:211], v[210:211], v[90:91]
	s_nop 0
	v_mfma_f32_16x16x4_f32 v[72:75], v140, v208, v[72:75]
	s_waitcnt lgkmcnt(2)
	v_pk_mul_f32 v[212:213], v[212:213], v[92:93]
	v_mfma_f32_16x16x4_f32 v[244:247], v141, v209, 0
	v_pk_mul_f32 v[214:215], v[214:215], v[94:95]
	v_mfma_f32_16x16x4_f32 v[72:75], v142, v210, v[72:75]
	s_waitcnt lgkmcnt(1)
	v_pk_mul_f32 v[216:217], v[216:217], v[96:97]
	v_mfma_f32_16x16x4_f32 v[244:247], v143, v211, v[244:247]
	v_pk_mul_f32 v[218:219], v[218:219], v[98:99]
	v_mfma_f32_16x16x4_f32 v[72:75], v144, v212, v[72:75]
	s_waitcnt lgkmcnt(0)
	v_pk_mul_f32 v[220:221], v[220:221], v[100:101]
	v_mfma_f32_16x16x4_f32 v[244:247], v145, v213, v[244:247]
	v_pk_mul_f32 v[222:223], v[222:223], v[102:103]
	v_mfma_f32_16x16x4_f32 v[72:75], v146, v214, v[72:75]
	s_mov_b64 exec, s[98:99]
	ds_write_b32 v231, v248
	ds_write_b32 v231, v249 offset:256
	ds_write_b32 v231, v250 offset:512
	ds_write_b32 v231, v251 offset:768
	s_mov_b64 exec, -1
	ds_read_b64 v[186:187], v34 offset:9984
	ds_read_b64 v[190:191], v34 offset:11008
	v_mfma_f32_16x16x4_f32 v[244:247], v147, v215, v[244:247]
	ds_read_b64 v[194:195], v34 offset:12032
	ds_read_b64 v[198:199], v34 offset:13056
	v_mfma_f32_16x16x4_f32 v[72:75], v148, v216, v[72:75]
	ds_read_b64 v[184:185], v236 offset:9984
	ds_read_b64 v[188:189], v236 offset:11008
	ds_read_b64 v[80:81], v32
	v_mfma_f32_16x16x4_f32 v[244:247], v149, v217, v[244:247]
	ds_read_b64 v[82:83], v33
	ds_read_b32 v36, v239 offset:4096
	ds_read_b64 v[192:193], v236 offset:12032
	v_mfma_f32_16x16x4_f32 v[72:75], v150, v218, v[72:75]
	ds_read_b64 v[196:197], v236 offset:13056
	ds_read_b32 v37, v239 offset:4352
	ds_read_b128 v[88:91], v26
	v_mfma_f32_16x16x4_f32 v[244:247], v151, v219, v[244:247]
	ds_read_b128 v[92:95], v26 offset:1024
	ds_read_b128 v[96:99], v26 offset:2048
	ds_read_b128 v[100:103], v26 offset:3072
	v_mfma_f32_16x16x4_f32 v[72:75], v152, v220, v[72:75]
	ds_read_b32 v104, v29 offset:4
	ds_read_b32 v105, v29 offset:76
	ds_read_b64 v[106:107], v29 offset:8
	v_mfma_f32_16x16x4_f32 v[244:247], v153, v221, v[244:247]
	ds_read_b64 v[108:109], v29 offset:40
	ds_read_b32 v126, v31 offset:4
	ds_read_b32 v127, v31 offset:76
	v_mfma_f32_16x16x4_f32 v[72:75], v154, v222, v[72:75]
	ds_read_b64 v[128:129], v31 offset:8
	ds_read_b64 v[130:131], v31 offset:40
	ds_read_b64 v[110:111], v30
	v_mfma_f32_16x16x4_f32 v[244:247], v155, v223, v[244:247]
	ds_read_b64 v[112:113], v30 offset:32
	ds_read_b64 v[114:115], v30 offset:64
	ds_read_b64 v[116:117], v30 offset:96
	ds_read_b64 v[118:119], v30 offset:8
	ds_read_b64 v[120:121], v30 offset:40
	ds_read_b64 v[122:123], v30 offset:72
	ds_read_b64 v[124:125], v30 offset:104
	s_waitcnt lgkmcnt(15)
	v_mfma_f32_16x16x4_f32 v[208:211], v186, v38, v[208:211]
	s_nop 1
	v_pk_add_f32 v[72:73], v[72:73], v[244:245]
	v_pk_add_f32 v[74:75], v[74:75], v[246:247]
	v_fmac_f32_e32 v73, v156, v72
	v_mfma_f32_16x16x4_f32 v[212:215], v190, v38, v[212:215]
	v_pk_fma_f32 v[74:75], v[158:159], v[72:73], v[74:75] op_sel:[0,0,0] op_sel_hi:[1,0,1]
	v_pk_fma_f32 v[74:75], v[160:161], v[72:73], v[74:75] op_sel:[0,1,0] op_sel_hi:[1,1,1]
	v_fmac_f32_e32 v75, v157, v74
	v_mfma_f32_16x16x4_f32 v[216:219], v194, v38, v[216:219]
	v_mov_b32_e32 v44, v72
	v_mov_b32_e32 v45, v73
	v_mov_b32_e32 v60, v74
	v_mfma_f32_16x16x4_f32 v[240:243], v80, v36, 0
	v_mov_b32_e32 v61, v75
	v_permlane16_swap_b32_e32 v204, v44
	v_permlane16_swap_b32_e32 v205, v45
	v_mfma_f32_16x16x4_f32 v[240:243], v81, v37, v[240:243]
	v_permlane16_swap_b32_e32 v206, v60
	v_permlane16_swap_b32_e32 v207, v61
	v_pk_fma_f32 v[72:73], v[162:163], v[204:205], v[72:73] op_sel:[0,0,0] op_sel_hi:[1,0,1]
	v_mfma_f32_16x16x4_f32 v[220:223], v198, v38, v[220:223]
	v_pk_fma_f32 v[72:73], v[164:165], v[204:205], v[72:73] op_sel:[0,1,0] op_sel_hi:[1,1,1]
	v_pk_fma_f32 v[72:73], v[166:167], v[206:207], v[72:73] op_sel:[0,0,0] op_sel_hi:[1,0,1]
	v_pk_fma_f32 v[72:73], v[168:169], v[206:207], v[72:73] op_sel:[0,1,0] op_sel_hi:[1,1,1]
	v_mfma_f32_16x16x4_f32 v[208:211], v187, v39, v[208:211]
	v_pk_fma_f32 v[74:75], v[170:171], v[204:205], v[74:75] op_sel:[0,0,0] op_sel_hi:[1,0,1]
	v_pk_fma_f32 v[74:75], v[172:173], v[204:205], v[74:75] op_sel:[0,1,0] op_sel_hi:[1,1,1]
	v_pk_fma_f32 v[74:75], v[174:175], v[206:207], v[74:75] op_sel:[0,0,0] op_sel_hi:[1,0,1]
	v_mfma_f32_16x16x4_f32 v[212:215], v191, v39, v[212:215]
	v_pk_fma_f32 v[74:75], v[176:177], v[206:207], v[74:75] op_sel:[0,1,0] op_sel_hi:[1,1,1]
	v_fmac_f32_e32 v73, v178, v72
	v_pk_fma_f32 v[74:75], v[180:181], v[72:73], v[74:75] op_sel:[0,0,0] op_sel_hi:[1,0,1]
	v_mfma_f32_16x16x4_f32 v[216:219], v195, v39, v[216:219]
	v_pk_fma_f32 v[74:75], v[182:183], v[72:73], v[74:75] op_sel:[0,1,0] op_sel_hi:[1,1,1]
	v_fmac_f32_e32 v75, v179, v74
	v_mov_b32_e32 v252, v72
	v_mfma_f32_16x16x4_f32 v[220:223], v199, v39, v[220:223]
	v_mov_b32_e32 v253, v73
	v_mov_b32_e32 v254, v74
	v_mov_b32_e32 v255, v75
	s_nop 0
	v_permlane32_swap_b32_e32 v252, v254
	v_permlane32_swap_b32_e32 v253, v255
	s_nop 0
	v_mfma_f32_16x16x4_f32 v[208:211], v184, v252, v[208:211]
	ds_read_b128 v[140:143], v226 offset:9984
	v_mfma_f32_16x16x4_f32 v[212:215], v188, v252, v[212:215]
	ds_read_b128 v[144:147], v226 offset:10048
	v_mfma_f32_16x16x4_f32 v[216:219], v192, v252, v[216:219]
	ds_read_b128 v[148:151], v226 offset:10112
	v_mfma_f32_16x16x4_f32 v[220:223], v196, v252, v[220:223]
	ds_read_b128 v[152:155], v226 offset:10176
	v_mfma_f32_16x16x4_f32 v[208:211], v185, v253, v[208:211]
	v_mfma_f32_16x16x4_f32 v[212:215], v189, v253, v[212:215]
	v_mfma_f32_16x16x4_f32 v[216:219], v193, v253, v[216:219]
	v_mfma_f32_16x16x4_f32 v[220:223], v197, v253, v[220:223]
	v_mfma_f32_16x16x4_f32 v[248:251], v134, v252, v[72:75]
	v_mfma_f32_16x16x4_f32 v[248:251], v135, v253, v[248:251]
	s_waitcnt lgkmcnt(3)
	v_pk_mul_f32 v[208:209], v[208:209], v[140:141]
	v_pk_mul_f32 v[210:211], v[210:211], v[142:143]
	s_nop 0
	v_mfma_f32_16x16x4_f32 v[240:243], v88, v208, v[240:243]
	s_waitcnt lgkmcnt(2)
	v_pk_mul_f32 v[212:213], v[212:213], v[144:145]
	v_mfma_f32_16x16x4_f32 v[244:247], v89, v209, 0
	v_pk_mul_f32 v[214:215], v[214:215], v[146:147]
	v_mfma_f32_16x16x4_f32 v[240:243], v90, v210, v[240:243]
	s_waitcnt lgkmcnt(1)
	v_pk_mul_f32 v[216:217], v[216:217], v[148:149]
	v_mfma_f32_16x16x4_f32 v[244:247], v91, v211, v[244:247]
	v_pk_mul_f32 v[218:219], v[218:219], v[150:151]
	v_mfma_f32_16x16x4_f32 v[240:243], v92, v212, v[240:243]
	s_waitcnt lgkmcnt(0)
	v_pk_mul_f32 v[220:221], v[220:221], v[152:153]
	v_mfma_f32_16x16x4_f32 v[244:247], v93, v213, v[244:247]
	v_pk_mul_f32 v[222:223], v[222:223], v[154:155]
	v_mfma_f32_16x16x4_f32 v[240:243], v94, v214, v[240:243]
	s_mov_b64 exec, s[98:99]
	ds_write_b32 v231, v248 offset:2048
	ds_write_b32 v231, v249 offset:2304
	ds_write_b32 v231, v250 offset:2560
	ds_write_b32 v231, v251 offset:2816
	s_mov_b64 exec, -1
	ds_read_b64 v[186:187], v35
	ds_read_b64 v[190:191], v35 offset:1024
	v_mfma_f32_16x16x4_f32 v[244:247], v95, v215, v[244:247]
	ds_read_b64 v[194:195], v35 offset:2048
	ds_read_b64 v[198:199], v35 offset:3072
	v_mfma_f32_16x16x4_f32 v[240:243], v96, v216, v[240:243]
	ds_read_b64 v[184:185], v27
	ds_read_b64 v[188:189], v27 offset:1024
	ds_read_b64 v[132:133], v32 offset:9984
	v_mfma_f32_16x16x4_f32 v[244:247], v97, v217, v[244:247]
	ds_read_b64 v[134:135], v33 offset:9984
	ds_read_b32 v38, v239 offset:6144
	ds_read_b64 v[192:193], v27 offset:2048
	v_mfma_f32_16x16x4_f32 v[240:243], v98, v218, v[240:243]
	ds_read_b64 v[196:197], v27 offset:3072
	ds_read_b32 v39, v239 offset:6400
	ds_read_b128 v[140:143], v26 offset:9984
	v_mfma_f32_16x16x4_f32 v[244:247], v99, v219, v[244:247]
	ds_read_b128 v[144:147], v26 offset:11008
	ds_read_b128 v[148:151], v26 offset:12032
	ds_read_b128 v[152:155], v26 offset:13056
	v_mfma_f32_16x16x4_f32 v[240:243], v100, v220, v[240:243]
	ds_read_b32 v156, v29 offset:9988
	ds_read_b32 v157, v29 offset:10060
	ds_read_b64 v[158:159], v29 offset:9992
	v_mfma_f32_16x16x4_f32 v[244:247], v101, v221, v[244:247]
	ds_read_b64 v[160:161], v29 offset:10024
	ds_read_b32 v178, v31 offset:9988
	ds_read_b32 v179, v31 offset:10060
	v_mfma_f32_16x16x4_f32 v[240:243], v102, v222, v[240:243]
	ds_read_b64 v[180:181], v31 offset:9992
	ds_read_b64 v[182:183], v31 offset:10024
	ds_read_b64 v[162:163], v30 offset:9984
	v_mfma_f32_16x16x4_f32 v[244:247], v103, v223, v[244:247]
	ds_read_b64 v[164:165], v30 offset:10016
	ds_read_b64 v[166:167], v30 offset:10048
	ds_read_b64 v[168:169], v30 offset:10080
	ds_read_b64 v[170:171], v30 offset:9992
	ds_read_b64 v[172:173], v30 offset:10024
	ds_read_b64 v[174:175], v30 offset:10056
	ds_read_b64 v[176:177], v30 offset:10088
	s_waitcnt lgkmcnt(15)
	v_mfma_f32_16x16x4_f32 v[208:211], v186, v36, v[208:211]
	s_nop 1
	v_pk_add_f32 v[240:241], v[240:241], v[244:245]
	v_pk_add_f32 v[242:243], v[242:243], v[246:247]
	v_fmac_f32_e32 v241, v104, v240
	v_mfma_f32_16x16x4_f32 v[212:215], v190, v36, v[212:215]
	v_pk_fma_f32 v[242:243], v[106:107], v[240:241], v[242:243] op_sel:[0,0,0] op_sel_hi:[1,0,1]
	v_pk_fma_f32 v[242:243], v[108:109], v[240:241], v[242:243] op_sel:[0,1,0] op_sel_hi:[1,1,1]
	v_fmac_f32_e32 v243, v105, v242
	v_mfma_f32_16x16x4_f32 v[216:219], v194, v36, v[216:219]
	v_mov_b32_e32 v44, v240
	v_mov_b32_e32 v45, v241
	v_mov_b32_e32 v60, v242
	v_mfma_f32_16x16x4_f32 v[72:75], v132, v38, 0
	v_mov_b32_e32 v61, v243
	v_permlane16_swap_b32_e32 v204, v44
	v_permlane16_swap_b32_e32 v205, v45
	v_mfma_f32_16x16x4_f32 v[72:75], v133, v39, v[72:75]
	v_permlane16_swap_b32_e32 v206, v60
	v_permlane16_swap_b32_e32 v207, v61
	v_pk_fma_f32 v[240:241], v[110:111], v[204:205], v[240:241] op_sel:[0,0,0] op_sel_hi:[1,0,1]
	v_mfma_f32_16x16x4_f32 v[220:223], v198, v36, v[220:223]
	v_pk_fma_f32 v[240:241], v[112:113], v[204:205], v[240:241] op_sel:[0,1,0] op_sel_hi:[1,1,1]
	v_pk_fma_f32 v[240:241], v[114:115], v[206:207], v[240:241] op_sel:[0,0,0] op_sel_hi:[1,0,1]
	v_pk_fma_f32 v[240:241], v[116:117], v[206:207], v[240:241] op_sel:[0,1,0] op_sel_hi:[1,1,1]
	v_mfma_f32_16x16x4_f32 v[208:211], v187, v37, v[208:211]
	v_pk_fma_f32 v[242:243], v[118:119], v[204:205], v[242:243] op_sel:[0,0,0] op_sel_hi:[1,0,1]
	v_pk_fma_f32 v[242:243], v[120:121], v[204:205], v[242:243] op_sel:[0,1,0] op_sel_hi:[1,1,1]
	v_pk_fma_f32 v[242:243], v[122:123], v[206:207], v[242:243] op_sel:[0,0,0] op_sel_hi:[1,0,1]
	v_mfma_f32_16x16x4_f32 v[212:215], v191, v37, v[212:215]
	v_pk_fma_f32 v[242:243], v[124:125], v[206:207], v[242:243] op_sel:[0,1,0] op_sel_hi:[1,1,1]
	v_fmac_f32_e32 v241, v126, v240
	v_pk_fma_f32 v[242:243], v[128:129], v[240:241], v[242:243] op_sel:[0,0,0] op_sel_hi:[1,0,1]
	v_mfma_f32_16x16x4_f32 v[216:219], v195, v37, v[216:219]
	v_pk_fma_f32 v[242:243], v[130:131], v[240:241], v[242:243] op_sel:[0,1,0] op_sel_hi:[1,1,1]
	v_fmac_f32_e32 v243, v127, v242
	v_mov_b32_e32 v252, v240
	v_mfma_f32_16x16x4_f32 v[220:223], v199, v37, v[220:223]
	v_mov_b32_e32 v253, v241
	v_mov_b32_e32 v254, v242
	v_mov_b32_e32 v255, v243
	s_nop 0
	v_permlane32_swap_b32_e32 v252, v254
	v_permlane32_swap_b32_e32 v253, v255
	s_nop 0
	v_mfma_f32_16x16x4_f32 v[208:211], v184, v252, v[208:211]
	ds_read_b128 v[88:91], v28
	v_mfma_f32_16x16x4_f32 v[212:215], v188, v252, v[212:215]
	ds_read_b128 v[92:95], v28 offset:64
	v_mfma_f32_16x16x4_f32 v[216:219], v192, v252, v[216:219]
	ds_read_b128 v[96:99], v28 offset:128
	v_mfma_f32_16x16x4_f32 v[220:223], v196, v252, v[220:223]
	ds_read_b128 v[100:103], v28 offset:192
	v_mfma_f32_16x16x4_f32 v[208:211], v185, v253, v[208:211]
	v_mfma_f32_16x16x4_f32 v[212:215], v189, v253, v[212:215]
	v_mfma_f32_16x16x4_f32 v[216:219], v193, v253, v[216:219]
	v_mfma_f32_16x16x4_f32 v[220:223], v197, v253, v[220:223]
	v_mfma_f32_16x16x4_f32 v[248:251], v82, v252, v[240:243]
	v_mfma_f32_16x16x4_f32 v[248:251], v83, v253, v[248:251]
	s_waitcnt lgkmcnt(3)
	v_pk_mul_f32 v[208:209], v[208:209], v[88:89]
	v_pk_mul_f32 v[210:211], v[210:211], v[90:91]
	s_nop 0
	v_mfma_f32_16x16x4_f32 v[72:75], v140, v208, v[72:75]
	s_waitcnt lgkmcnt(2)
	v_pk_mul_f32 v[212:213], v[212:213], v[92:93]
	v_mfma_f32_16x16x4_f32 v[244:247], v141, v209, 0
	v_pk_mul_f32 v[214:215], v[214:215], v[94:95]
	v_mfma_f32_16x16x4_f32 v[72:75], v142, v210, v[72:75]
	s_waitcnt lgkmcnt(1)
	v_pk_mul_f32 v[216:217], v[216:217], v[96:97]
	v_mfma_f32_16x16x4_f32 v[244:247], v143, v211, v[244:247]
	v_pk_mul_f32 v[218:219], v[218:219], v[98:99]
	v_mfma_f32_16x16x4_f32 v[72:75], v144, v212, v[72:75]
	s_waitcnt lgkmcnt(0)
	v_pk_mul_f32 v[220:221], v[220:221], v[100:101]
	v_mfma_f32_16x16x4_f32 v[244:247], v145, v213, v[244:247]
	v_pk_mul_f32 v[222:223], v[222:223], v[102:103]
	v_mfma_f32_16x16x4_f32 v[72:75], v146, v214, v[72:75]
	s_mov_b64 exec, s[98:99]
	ds_write_b32 v231, v248 offset:4096
	ds_write_b32 v231, v249 offset:4352
	ds_write_b32 v231, v250 offset:4608
	ds_write_b32 v231, v251 offset:4864
	s_mov_b64 exec, -1
	ds_read_b64 v[186:187], v35 offset:9984
	ds_read_b64 v[190:191], v35 offset:11008
	v_mfma_f32_16x16x4_f32 v[244:247], v147, v215, v[244:247]
	ds_read_b64 v[194:195], v35 offset:12032
	ds_read_b64 v[198:199], v35 offset:13056
	v_mfma_f32_16x16x4_f32 v[72:75], v148, v216, v[72:75]
	ds_read_b64 v[184:185], v27 offset:9984
	ds_read_b64 v[188:189], v27 offset:11008
	v_mfma_f32_16x16x4_f32 v[244:247], v149, v217, v[244:247]
	ds_read_b64 v[192:193], v27 offset:12032
	ds_read_b64 v[196:197], v27 offset:13056
	v_mfma_f32_16x16x4_f32 v[72:75], v150, v218, v[72:75]
	v_mfma_f32_16x16x4_f32 v[244:247], v151, v219, v[244:247]
	v_mfma_f32_16x16x4_f32 v[72:75], v152, v220, v[72:75]
	v_mfma_f32_16x16x4_f32 v[244:247], v153, v221, v[244:247]
	v_mfma_f32_16x16x4_f32 v[72:75], v154, v222, v[72:75]
	v_mfma_f32_16x16x4_f32 v[244:247], v155, v223, v[244:247]
	s_waitcnt lgkmcnt(7)
	v_mfma_f32_16x16x4_f32 v[208:211], v186, v38, v[208:211]
	s_nop 2
	v_pk_add_f32 v[72:73], v[72:73], v[244:245]
	v_pk_add_f32 v[74:75], v[74:75], v[246:247]
	v_fmac_f32_e32 v73, v156, v72
	s_waitcnt lgkmcnt(6)
	v_mfma_f32_16x16x4_f32 v[212:215], v190, v38, v[212:215]
	v_pk_fma_f32 v[74:75], v[158:159], v[72:73], v[74:75] op_sel:[0,0,0] op_sel_hi:[1,0,1]
	v_pk_fma_f32 v[74:75], v[160:161], v[72:73], v[74:75] op_sel:[0,1,0] op_sel_hi:[1,1,1]
	v_fmac_f32_e32 v75, v157, v74
	s_waitcnt lgkmcnt(5)
	v_mfma_f32_16x16x4_f32 v[216:219], v194, v38, v[216:219]
	v_mov_b32_e32 v44, v72
	v_mov_b32_e32 v45, v73
	v_mov_b32_e32 v60, v74
	s_waitcnt lgkmcnt(4)
	v_mfma_f32_16x16x4_f32 v[220:223], v198, v38, v[220:223]
	v_mov_b32_e32 v61, v75
	v_permlane16_swap_b32_e32 v204, v44
	v_permlane16_swap_b32_e32 v205, v45
	v_mfma_f32_16x16x4_f32 v[208:211], v187, v39, v[208:211]
	v_permlane16_swap_b32_e32 v206, v60
	v_permlane16_swap_b32_e32 v207, v61
	v_pk_fma_f32 v[72:73], v[162:163], v[204:205], v[72:73] op_sel:[0,0,0] op_sel_hi:[1,0,1]
	v_mfma_f32_16x16x4_f32 v[212:215], v191, v39, v[212:215]
	v_pk_fma_f32 v[72:73], v[164:165], v[204:205], v[72:73] op_sel:[0,1,0] op_sel_hi:[1,1,1]
	v_pk_fma_f32 v[72:73], v[166:167], v[206:207], v[72:73] op_sel:[0,0,0] op_sel_hi:[1,0,1]
	v_pk_fma_f32 v[72:73], v[168:169], v[206:207], v[72:73] op_sel:[0,1,0] op_sel_hi:[1,1,1]
	v_mfma_f32_16x16x4_f32 v[216:219], v195, v39, v[216:219]
	v_pk_fma_f32 v[74:75], v[170:171], v[204:205], v[74:75] op_sel:[0,0,0] op_sel_hi:[1,0,1]
	v_pk_fma_f32 v[74:75], v[172:173], v[204:205], v[74:75] op_sel:[0,1,0] op_sel_hi:[1,1,1]
	v_pk_fma_f32 v[74:75], v[174:175], v[206:207], v[74:75] op_sel:[0,0,0] op_sel_hi:[1,0,1]
	v_mfma_f32_16x16x4_f32 v[220:223], v199, v39, v[220:223]
	v_pk_fma_f32 v[74:75], v[176:177], v[206:207], v[74:75] op_sel:[0,1,0] op_sel_hi:[1,1,1]
	v_fmac_f32_e32 v73, v178, v72
	v_pk_fma_f32 v[74:75], v[180:181], v[72:73], v[74:75] op_sel:[0,0,0] op_sel_hi:[1,0,1]
	v_pk_fma_f32 v[74:75], v[182:183], v[72:73], v[74:75] op_sel:[0,1,0] op_sel_hi:[1,1,1]
	v_fmac_f32_e32 v75, v179, v74
	v_mov_b32_e32 v252, v72
	v_mov_b32_e32 v253, v73
	v_mov_b32_e32 v254, v74
	v_mov_b32_e32 v255, v75
	s_nop 0
	v_permlane32_swap_b32_e32 v252, v254
	v_permlane32_swap_b32_e32 v253, v255
	s_waitcnt lgkmcnt(3)
	s_nop 0
	v_mfma_f32_16x16x4_f32 v[208:211], v184, v252, v[208:211]
	ds_read_b128 v[140:143], v28 offset:9984
	s_waitcnt lgkmcnt(3)
	v_mfma_f32_16x16x4_f32 v[212:215], v188, v252, v[212:215]
	ds_read_b128 v[144:147], v28 offset:10048
	s_waitcnt lgkmcnt(3)
	v_mfma_f32_16x16x4_f32 v[216:219], v192, v252, v[216:219]
	ds_read_b128 v[148:151], v28 offset:10112
	s_waitcnt lgkmcnt(3)
	v_mfma_f32_16x16x4_f32 v[220:223], v196, v252, v[220:223]
	ds_read_b128 v[152:155], v28 offset:10176
	v_mfma_f32_16x16x4_f32 v[208:211], v185, v253, v[208:211]
	v_mfma_f32_16x16x4_f32 v[212:215], v189, v253, v[212:215]
	v_mfma_f32_16x16x4_f32 v[216:219], v193, v253, v[216:219]
	v_mfma_f32_16x16x4_f32 v[220:223], v197, v253, v[220:223]
	v_mfma_f32_16x16x4_f32 v[248:251], v134, v252, v[72:75]
	v_mfma_f32_16x16x4_f32 v[248:251], v135, v253, v[248:251]
	s_waitcnt lgkmcnt(3)
	v_pk_mul_f32 v[208:209], v[208:209], v[140:141]
	v_pk_mul_f32 v[210:211], v[210:211], v[142:143]
	s_waitcnt lgkmcnt(2)
	v_pk_mul_f32 v[212:213], v[212:213], v[144:145]
	v_pk_mul_f32 v[214:215], v[214:215], v[146:147]
	s_waitcnt lgkmcnt(1)
	v_pk_mul_f32 v[216:217], v[216:217], v[148:149]
	v_pk_mul_f32 v[218:219], v[218:219], v[150:151]
	s_waitcnt lgkmcnt(0)
	v_pk_mul_f32 v[220:221], v[220:221], v[152:153]
	v_pk_mul_f32 v[222:223], v[222:223], v[154:155]
	s_mov_b64 exec, s[98:99]
	s_nop 0
	ds_write_b32 v231, v248 offset:6144
	ds_write_b32 v231, v249 offset:6400
	ds_write_b32 v231, v250 offset:6656
	ds_write_b32 v231, v251 offset:6912
	s_mov_b64 exec, -1
	s_branch .LBB0_655
